# K2 + write-through (sc1) on the 16-byte GEMM epilogue stores so the grid barrier's L2 write-back has less to flush
# speedup vs baseline: 1.0645x; 1.0026x over previous
.LBB0_116:
	v_mbcnt_lo_u32_b32 v137, -1, 0
	v_mbcnt_hi_u32_b32 v137, -1, v137
	s_lshl_b32 s0, s39, 8
	s_nop 0
	v_ashrrev_i32_e32 v136, 1, v137
	v_and_or_b32 v137, v137, 15, s81
	v_and_b32_e32 v136, -8, v136
	s_or_b32 s0, s0, s82
	v_lshl_add_u32 v142, s38, 8, v137
	v_mov_b64_e32 v[138:139], s[10:11]
	v_add_u32_e32 v136, s0, v136
	v_mad_i64_i32 v[138:139], s[0:1], v142, s29, v[138:139]
	v_ashrrev_i32_e32 v137, 31, v136
	s_movk_i32 s0, 0x300
	v_lshl_add_u64 v[138:139], v[136:137], 1, v[138:139]
	v_cmp_gt_i32_e32 vcc, s0, v136
	s_and_saveexec_b64 s[0:1], vcc
	s_cbranch_execz .LBB0_118
	v_cvt_pk_bf16_f32 v118, v118, v119
	v_cvt_pk_bf16_f32 v119, v120, v121
	v_cvt_pk_bf16_f32 v120, v114, v115
	v_cvt_pk_bf16_f32 v121, v116, v117
	flat_store_dwordx4 v[138:139], v[118:121] sc1
.LBB0_118:
	s_or_b64 exec, exec, s[0:1]
	v_cmp_gt_i32_e64 s[0:1], s97, v136
	s_mov_b64 s[34:35], exec
	s_and_b64 s[26:27], s[34:35], s[0:1]
	s_mov_b32 s77, 0x5f00000
	v_mov_b64_e32 v[246:247], v[216:217]
	v_mov_b64_e32 v[248:249], v[218:219]
	v_mov_b32_e32 v218, 0x358637bd
	s_mov_b64 exec, s[26:27]
	s_cbranch_execz .LBB0_120
	v_cvt_pk_bf16_f32 v114, v126, v127
	v_cvt_pk_bf16_f32 v115, v128, v129
	v_cvt_pk_bf16_f32 v116, v122, v123
	v_cvt_pk_bf16_f32 v117, v124, v125
	flat_store_dwordx4 v[138:139], v[114:117] offset:256 sc1
.LBB0_120:
	s_or_b64 exec, exec, s[34:35]
	s_nop 0
	v_or_b32_e32 v116, 16, v142
	v_mov_b64_e32 v[114:115], s[10:11]
	v_mad_i64_i32 v[114:115], s[26:27], v116, s29, v[114:115]
	v_lshl_add_u64 v[114:115], v[136:137], 1, v[114:115]
	s_and_saveexec_b64 s[34:35], vcc
	s_cbranch_execz .LBB0_122
	v_cvt_pk_bf16_f32 v102, v102, v103
	v_cvt_pk_bf16_f32 v103, v104, v105
	v_cvt_pk_bf16_f32 v104, v98, v99
	v_cvt_pk_bf16_f32 v105, v100, v101
	flat_store_dwordx4 v[114:115], v[102:105] sc1
.LBB0_122:
	s_or_b64 exec, exec, s[34:35]
	s_and_saveexec_b64 s[34:35], s[0:1]
	s_cbranch_execz .LBB0_124
	v_cvt_pk_bf16_f32 v98, v110, v111
	v_cvt_pk_bf16_f32 v99, v112, v113
	v_cvt_pk_bf16_f32 v100, v106, v107
	v_cvt_pk_bf16_f32 v101, v108, v109
	flat_store_dwordx4 v[114:115], v[98:101] offset:256 sc1
.LBB0_124:
	s_or_b64 exec, exec, s[34:35]
	s_nop 0
	v_or_b32_e32 v100, 32, v142
	v_mov_b64_e32 v[98:99], s[10:11]
	v_mad_i64_i32 v[98:99], s[26:27], v100, s29, v[98:99]
	v_lshl_add_u64 v[98:99], v[136:137], 1, v[98:99]
	s_and_saveexec_b64 s[34:35], vcc
	s_cbranch_execz .LBB0_126
	v_cvt_pk_bf16_f32 v86, v86, v87
	v_cvt_pk_bf16_f32 v87, v88, v89
	v_cvt_pk_bf16_f32 v88, v82, v83
	v_cvt_pk_bf16_f32 v89, v84, v85
	flat_store_dwordx4 v[98:99], v[86:89] sc1
.LBB0_126:
	s_or_b64 exec, exec, s[34:35]
	s_and_saveexec_b64 s[34:35], s[0:1]
	s_cbranch_execz .LBB0_128
	v_cvt_pk_bf16_f32 v82, v94, v95
	v_cvt_pk_bf16_f32 v83, v96, v97
	v_cvt_pk_bf16_f32 v84, v90, v91
	v_cvt_pk_bf16_f32 v85, v92, v93
	flat_store_dwordx4 v[98:99], v[82:85] offset:256 sc1
.LBB0_128:
	s_or_b64 exec, exec, s[34:35]
	s_nop 0
	v_or_b32_e32 v84, 48, v142
	v_mov_b64_e32 v[82:83], s[10:11]
	v_mad_i64_i32 v[82:83], s[26:27], v84, s29, v[82:83]
	v_lshl_add_u64 v[82:83], v[136:137], 1, v[82:83]
	s_and_saveexec_b64 s[34:35], vcc
	s_cbranch_execz .LBB0_130
	v_cvt_pk_bf16_f32 v56, v56, v57
	v_cvt_pk_bf16_f32 v57, v58, v59
	v_cvt_pk_bf16_f32 v58, v48, v49
	v_cvt_pk_bf16_f32 v59, v50, v51
	flat_store_dwordx4 v[82:83], v[56:59] sc1
.LBB0_130:
	s_or_b64 exec, exec, s[34:35]
	s_and_saveexec_b64 s[34:35], s[0:1]
	s_cbranch_execz .LBB0_132
	v_cvt_pk_bf16_f32 v48, v72, v73
	v_cvt_pk_bf16_f32 v49, v74, v75
	v_cvt_pk_bf16_f32 v50, v64, v65
	v_cvt_pk_bf16_f32 v51, v66, v67
	flat_store_dwordx4 v[82:83], v[48:51] offset:256 sc1
.LBB0_132:
	s_or_b64 exec, exec, s[34:35]
	s_nop 0
	v_add_u32_e32 v50, 0x80, v142
	v_mov_b64_e32 v[48:49], s[10:11]
	v_mad_i64_i32 v[48:49], s[26:27], v50, s29, v[48:49]
	v_lshl_add_u64 v[48:49], v[136:137], 1, v[48:49]
	s_and_saveexec_b64 s[34:35], vcc
	s_cbranch_execz .LBB0_134
	v_cvt_pk_bf16_f32 v50, v60, v61
	v_cvt_pk_bf16_f32 v51, v62, v63
	v_cvt_pk_bf16_f32 v52, v52, v53
	v_cvt_pk_bf16_f32 v53, v54, v55
	flat_store_dwordx4 v[48:49], v[50:53] sc1
.LBB0_134:
	s_or_b64 exec, exec, s[34:35]
	s_and_saveexec_b64 s[34:35], s[0:1]
	s_cbranch_execz .LBB0_136
	v_cvt_pk_bf16_f32 v50, v76, v77
	v_cvt_pk_bf16_f32 v51, v78, v79
	v_cvt_pk_bf16_f32 v52, v68, v69
	v_cvt_pk_bf16_f32 v53, v70, v71
	flat_store_dwordx4 v[48:49], v[50:53] offset:256 sc1
.LBB0_136:
	s_or_b64 exec, exec, s[34:35]
	s_nop 0
	v_add_u32_e32 v50, 0x90, v142
	v_mov_b64_e32 v[48:49], s[10:11]
	v_mad_i64_i32 v[48:49], s[26:27], v50, s29, v[48:49]
	v_lshl_add_u64 v[48:49], v[136:137], 1, v[48:49]
	s_and_saveexec_b64 s[34:35], vcc
	s_cbranch_execz .LBB0_138
	v_cvt_pk_bf16_f32 v36, v36, v37
	v_cvt_pk_bf16_f32 v37, v38, v39
	v_cvt_pk_bf16_f32 v38, v32, v33
	v_cvt_pk_bf16_f32 v39, v34, v35
	flat_store_dwordx4 v[48:49], v[36:39] sc1
.LBB0_138:
	s_or_b64 exec, exec, s[34:35]
	s_and_saveexec_b64 s[34:35], s[0:1]
	s_cbranch_execz .LBB0_140
	v_cvt_pk_bf16_f32 v32, v44, v45
	v_cvt_pk_bf16_f32 v33, v46, v47
	v_cvt_pk_bf16_f32 v34, v40, v41
	v_cvt_pk_bf16_f32 v35, v42, v43
	flat_store_dwordx4 v[48:49], v[32:35] offset:256 sc1
.LBB0_140:
	s_or_b64 exec, exec, s[34:35]
	s_nop 0
	v_add_u32_e32 v34, 0xa0, v142
	v_mov_b64_e32 v[32:33], s[10:11]
	v_mad_i64_i32 v[32:33], s[26:27], v34, s29, v[32:33]
	v_lshl_add_u64 v[32:33], v[136:137], 1, v[32:33]
	s_and_saveexec_b64 s[34:35], vcc
	s_cbranch_execz .LBB0_142
	v_cvt_pk_bf16_f32 v20, v20, v21
	v_cvt_pk_bf16_f32 v21, v22, v23
	v_cvt_pk_bf16_f32 v22, v16, v17
	v_cvt_pk_bf16_f32 v23, v18, v19
	flat_store_dwordx4 v[32:33], v[20:23] sc1
.LBB0_142:
	s_or_b64 exec, exec, s[34:35]
	s_and_saveexec_b64 s[34:35], s[0:1]
	s_cbranch_execz .LBB0_144
	v_cvt_pk_bf16_f32 v16, v28, v29
	v_cvt_pk_bf16_f32 v17, v30, v31
	v_cvt_pk_bf16_f32 v18, v24, v25
	v_cvt_pk_bf16_f32 v19, v26, v27
	flat_store_dwordx4 v[32:33], v[16:19] offset:256 sc1

.LBB0_147:
	v_cvt_pk_bf16_f32 v4, v4, v5
	v_cvt_pk_bf16_f32 v5, v6, v7
	v_cvt_pk_bf16_f32 v6, v0, v1
	v_cvt_pk_bf16_f32 v7, v2, v3
	flat_store_dwordx4 v[16:17], v[4:7] sc1
	s_or_b64 exec, exec, s[34:35]
	s_and_saveexec_b64 s[34:35], s[0:1]
	s_cbranch_execz .LBB0_146
.LBB0_148:
	v_cvt_pk_bf16_f32 v0, v12, v13
	v_cvt_pk_bf16_f32 v1, v14, v15
	v_cvt_pk_bf16_f32 v2, v8, v9
	v_cvt_pk_bf16_f32 v3, v10, v11
	flat_store_dwordx4 v[16:17], v[0:3] offset:256 sc1
	s_or_b64 exec, exec, s[34:35]
	s_and_b64 vcc, exec, s[36:37]
	s_mov_b64 s[0:1], -1
	s_cbranch_vccnz .LBB0_107

.LBB0_237:
	s_lshl_b32 s6, s78, 8
	v_mbcnt_lo_u32_b32 v141, -1, 0
	v_mbcnt_hi_u32_b32 v141, -1, v141
	s_add_i32 s6, s6, s71
	v_and_or_b32 v140, v141, 15, s6
	s_lshl_b32 s6, s77, 8
	v_ashrrev_i32_e32 v141, 1, v141
	s_or_b32 s6, s6, s81
	v_and_b32_e32 v141, -8, v141
	v_add_u32_e32 v142, s6, v141
	v_ashrrev_i32_e32 v141, 31, v140
	v_lshlrev_b64 v[144:145], 13, v[140:141]
	v_ashrrev_i32_e32 v143, 31, v142
	v_lshl_add_u64 v[144:145], s[4:5], 0, v[144:145]
	s_movk_i32 s6, 0x1000
	v_lshl_add_u64 v[144:145], v[142:143], 1, v[144:145]
	v_cmp_gt_i32_e32 vcc, s6, v142
	s_and_saveexec_b64 s[6:7], vcc
	s_cbranch_execz .LBB0_239
	v_max_f32_e32 v122, v122, v122
	v_max_f32_e32 v123, v123, v123
	v_max_f32_e32 v124, v124, v124
	v_max_f32_e32 v122, 0, v122
	v_max_f32_e32 v123, 0, v123
	v_max_f32_e32 v124, 0, v124
	v_mul_f32_e32 v148, v122, v122
	v_max_f32_e32 v122, v127, v127
	v_mul_f32_e32 v127, v123, v123
	v_max_f32_e32 v123, v128, v128
	v_mul_f32_e32 v128, v124, v124
	v_max_f32_e32 v124, v129, v129
	v_max_f32_e32 v125, v125, v125
	v_max_f32_e32 v126, v126, v126
	v_max_f32_e32 v122, 0, v122
	v_max_f32_e32 v123, 0, v123
	v_max_f32_e32 v124, 0, v124
	v_max_f32_e32 v125, 0, v125
	v_max_f32_e32 v126, 0, v126
	v_mul_f32_e32 v122, v122, v122
	v_mul_f32_e32 v123, v123, v123
	v_mul_f32_e32 v124, v124, v124
	v_mul_f32_e32 v125, v125, v125
	v_mul_f32_e32 v126, v126, v126
	v_cvt_pk_bf16_f32 v122, v126, v122
	v_cvt_pk_bf16_f32 v123, v123, v124
	v_cvt_pk_bf16_f32 v124, v148, v127
	v_cvt_pk_bf16_f32 v125, v128, v125
	flat_store_dwordx4 v[144:145], v[122:125] sc1
.LBB0_239:
	s_or_b64 exec, exec, s[6:7]
	v_cmp_gt_i32_e64 s[38:39], s24, v142
	s_and_saveexec_b64 s[6:7], s[38:39]
	s_cbranch_execz .LBB0_241
	v_max_f32_e32 v114, v114, v114
	v_max_f32_e32 v115, v115, v115
	v_max_f32_e32 v116, v116, v116
	v_max_f32_e32 v114, 0, v114
	v_max_f32_e32 v115, 0, v115
	v_max_f32_e32 v116, 0, v116
	v_mul_f32_e32 v122, v114, v114
	v_max_f32_e32 v114, v119, v119
	v_mul_f32_e32 v119, v115, v115
	v_max_f32_e32 v115, v120, v120
	v_mul_f32_e32 v120, v116, v116
	v_max_f32_e32 v116, v121, v121
	v_max_f32_e32 v117, v117, v117
	v_max_f32_e32 v118, v118, v118
	v_max_f32_e32 v114, 0, v114
	v_max_f32_e32 v115, 0, v115
	v_max_f32_e32 v116, 0, v116
	v_max_f32_e32 v117, 0, v117
	v_max_f32_e32 v118, 0, v118
	v_mul_f32_e32 v114, v114, v114
	v_mul_f32_e32 v115, v115, v115
	v_mul_f32_e32 v116, v116, v116
	v_mul_f32_e32 v117, v117, v117
	v_mul_f32_e32 v118, v118, v118
	v_cvt_pk_bf16_f32 v114, v118, v114
	v_cvt_pk_bf16_f32 v115, v115, v116
	v_cvt_pk_bf16_f32 v116, v122, v119
	v_cvt_pk_bf16_f32 v117, v120, v117
	flat_store_dwordx4 v[144:145], v[114:117] offset:256 sc1
.LBB0_241:
	s_or_b64 exec, exec, s[6:7]
	s_nop 0
	v_or_b32_e32 v114, 16, v140
	v_ashrrev_i32_e32 v115, 31, v114
	v_lshlrev_b64 v[114:115], 13, v[114:115]
	v_lshl_add_u64 v[114:115], s[4:5], 0, v[114:115]
	v_lshl_add_u64 v[114:115], v[142:143], 1, v[114:115]
	s_and_saveexec_b64 s[6:7], vcc
	s_cbranch_execz .LBB0_243
	v_max_f32_e32 v106, v106, v106
	v_max_f32_e32 v107, v107, v107
	v_max_f32_e32 v108, v108, v108
	v_max_f32_e32 v106, 0, v106
	v_max_f32_e32 v107, 0, v107
	v_max_f32_e32 v108, 0, v108
	v_mul_f32_e32 v116, v106, v106
	v_max_f32_e32 v106, v111, v111
	v_mul_f32_e32 v111, v107, v107
	v_max_f32_e32 v107, v112, v112
	v_mul_f32_e32 v112, v108, v108
	v_max_f32_e32 v108, v113, v113
	v_max_f32_e32 v109, v109, v109
	v_max_f32_e32 v110, v110, v110
	v_max_f32_e32 v106, 0, v106
	v_max_f32_e32 v107, 0, v107
	v_max_f32_e32 v108, 0, v108
	v_max_f32_e32 v109, 0, v109
	v_max_f32_e32 v110, 0, v110
	v_mul_f32_e32 v106, v106, v106
	v_mul_f32_e32 v107, v107, v107
	v_mul_f32_e32 v108, v108, v108
	v_mul_f32_e32 v109, v109, v109
	v_mul_f32_e32 v110, v110, v110
	v_cvt_pk_bf16_f32 v106, v110, v106
	v_cvt_pk_bf16_f32 v107, v107, v108
	v_cvt_pk_bf16_f32 v108, v116, v111
	v_cvt_pk_bf16_f32 v109, v112, v109
	flat_store_dwordx4 v[114:115], v[106:109] sc1
.LBB0_243:
	s_or_b64 exec, exec, s[6:7]
	s_and_saveexec_b64 s[6:7], s[38:39]
	s_cbranch_execz .LBB0_245
	v_max_f32_e32 v98, v98, v98
	v_max_f32_e32 v99, v99, v99
	v_max_f32_e32 v100, v100, v100
	v_max_f32_e32 v98, 0, v98
	v_max_f32_e32 v99, 0, v99
	v_max_f32_e32 v100, 0, v100
	v_mul_f32_e32 v106, v98, v98
	v_max_f32_e32 v98, v103, v103
	v_mul_f32_e32 v103, v99, v99
	v_max_f32_e32 v99, v104, v104
	v_mul_f32_e32 v104, v100, v100
	v_max_f32_e32 v100, v105, v105
	v_max_f32_e32 v101, v101, v101
	v_max_f32_e32 v102, v102, v102
	v_max_f32_e32 v98, 0, v98
	v_max_f32_e32 v99, 0, v99
	v_max_f32_e32 v100, 0, v100
	v_max_f32_e32 v101, 0, v101
	v_max_f32_e32 v102, 0, v102
	v_mul_f32_e32 v98, v98, v98
	v_mul_f32_e32 v99, v99, v99
	v_mul_f32_e32 v100, v100, v100
	v_mul_f32_e32 v101, v101, v101
	v_mul_f32_e32 v102, v102, v102
	v_cvt_pk_bf16_f32 v98, v102, v98
	v_cvt_pk_bf16_f32 v99, v99, v100
	v_cvt_pk_bf16_f32 v100, v106, v103
	v_cvt_pk_bf16_f32 v101, v104, v101
	flat_store_dwordx4 v[114:115], v[98:101] offset:256 sc1
.LBB0_245:
	s_or_b64 exec, exec, s[6:7]
	s_nop 0
	v_or_b32_e32 v98, 32, v140
	v_ashrrev_i32_e32 v99, 31, v98
	v_lshlrev_b64 v[98:99], 13, v[98:99]
	v_lshl_add_u64 v[98:99], s[4:5], 0, v[98:99]
	v_lshl_add_u64 v[98:99], v[142:143], 1, v[98:99]
	s_and_saveexec_b64 s[6:7], vcc
	s_cbranch_execz .LBB0_247
	v_max_f32_e32 v90, v90, v90
	v_max_f32_e32 v91, v91, v91
	v_max_f32_e32 v92, v92, v92
	v_max_f32_e32 v90, 0, v90
	v_max_f32_e32 v91, 0, v91
	v_max_f32_e32 v92, 0, v92
	v_mul_f32_e32 v100, v90, v90
	v_max_f32_e32 v90, v95, v95
	v_mul_f32_e32 v95, v91, v91
	v_max_f32_e32 v91, v96, v96
	v_mul_f32_e32 v96, v92, v92
	v_max_f32_e32 v92, v97, v97
	v_max_f32_e32 v93, v93, v93
	v_max_f32_e32 v94, v94, v94
	v_max_f32_e32 v90, 0, v90
	v_max_f32_e32 v91, 0, v91
	v_max_f32_e32 v92, 0, v92
	v_max_f32_e32 v93, 0, v93
	v_max_f32_e32 v94, 0, v94
	v_mul_f32_e32 v90, v90, v90
	v_mul_f32_e32 v91, v91, v91
	v_mul_f32_e32 v92, v92, v92
	v_mul_f32_e32 v93, v93, v93
	v_mul_f32_e32 v94, v94, v94
	v_cvt_pk_bf16_f32 v90, v94, v90
	v_cvt_pk_bf16_f32 v91, v91, v92
	v_cvt_pk_bf16_f32 v92, v100, v95
	v_cvt_pk_bf16_f32 v93, v96, v93
	flat_store_dwordx4 v[98:99], v[90:93] sc1
.LBB0_247:
	s_or_b64 exec, exec, s[6:7]
	s_and_saveexec_b64 s[6:7], s[38:39]
	s_cbranch_execz .LBB0_249
	v_max_f32_e32 v82, v82, v82
	v_max_f32_e32 v83, v83, v83
	v_max_f32_e32 v84, v84, v84
	v_max_f32_e32 v82, 0, v82
	v_max_f32_e32 v83, 0, v83
	v_max_f32_e32 v84, 0, v84
	v_mul_f32_e32 v90, v82, v82
	v_max_f32_e32 v82, v87, v87
	v_mul_f32_e32 v87, v83, v83
	v_max_f32_e32 v83, v88, v88
	v_mul_f32_e32 v88, v84, v84
	v_max_f32_e32 v84, v89, v89
	v_max_f32_e32 v85, v85, v85
	v_max_f32_e32 v86, v86, v86
	v_max_f32_e32 v82, 0, v82
	v_max_f32_e32 v83, 0, v83
	v_max_f32_e32 v84, 0, v84
	v_max_f32_e32 v85, 0, v85
	v_max_f32_e32 v86, 0, v86
	v_mul_f32_e32 v82, v82, v82
	v_mul_f32_e32 v83, v83, v83
	v_mul_f32_e32 v84, v84, v84
	v_mul_f32_e32 v85, v85, v85
	v_mul_f32_e32 v86, v86, v86
	v_cvt_pk_bf16_f32 v82, v86, v82
	v_cvt_pk_bf16_f32 v83, v83, v84
	v_cvt_pk_bf16_f32 v84, v90, v87
	v_cvt_pk_bf16_f32 v85, v88, v85
	flat_store_dwordx4 v[98:99], v[82:85] offset:256 sc1
.LBB0_249:
	s_or_b64 exec, exec, s[6:7]
	s_nop 0
	v_or_b32_e32 v82, 48, v140
	v_ashrrev_i32_e32 v83, 31, v82
	v_lshlrev_b64 v[82:83], 13, v[82:83]
	v_lshl_add_u64 v[82:83], s[4:5], 0, v[82:83]
	v_lshl_add_u64 v[82:83], v[142:143], 1, v[82:83]
	s_and_saveexec_b64 s[6:7], vcc
	s_cbranch_execz .LBB0_251
	v_max_f32_e32 v72, v72, v72
	v_max_f32_e32 v73, v73, v73
	v_max_f32_e32 v74, v74, v74
	v_max_f32_e32 v72, 0, v72
	v_max_f32_e32 v73, 0, v73
	v_max_f32_e32 v74, 0, v74
	v_mul_f32_e32 v84, v72, v72
	v_max_f32_e32 v72, v77, v77
	v_mul_f32_e32 v77, v73, v73
	v_max_f32_e32 v73, v78, v78
	v_mul_f32_e32 v78, v74, v74
	v_max_f32_e32 v74, v79, v79
	v_max_f32_e32 v75, v75, v75
	v_max_f32_e32 v76, v76, v76
	v_max_f32_e32 v72, 0, v72
	v_max_f32_e32 v73, 0, v73
	v_max_f32_e32 v74, 0, v74
	v_max_f32_e32 v75, 0, v75
	v_max_f32_e32 v76, 0, v76
	v_mul_f32_e32 v72, v72, v72
	v_mul_f32_e32 v73, v73, v73
	v_mul_f32_e32 v74, v74, v74
	v_mul_f32_e32 v75, v75, v75
	v_mul_f32_e32 v76, v76, v76
	v_cvt_pk_bf16_f32 v72, v76, v72
	v_cvt_pk_bf16_f32 v73, v73, v74
	v_cvt_pk_bf16_f32 v74, v84, v77
	v_cvt_pk_bf16_f32 v75, v78, v75
	flat_store_dwordx4 v[82:83], v[72:75] sc1
.LBB0_251:
	s_or_b64 exec, exec, s[6:7]
	s_and_saveexec_b64 s[6:7], s[38:39]
	s_cbranch_execz .LBB0_253
	v_max_f32_e32 v64, v64, v64
	v_max_f32_e32 v65, v65, v65
	v_max_f32_e32 v66, v66, v66
	v_max_f32_e32 v64, 0, v64
	v_max_f32_e32 v65, 0, v65
	v_max_f32_e32 v66, 0, v66
	v_mul_f32_e32 v72, v64, v64
	v_max_f32_e32 v64, v69, v69
	v_mul_f32_e32 v69, v65, v65
	v_max_f32_e32 v65, v70, v70
	v_mul_f32_e32 v70, v66, v66
	v_max_f32_e32 v66, v71, v71
	v_max_f32_e32 v67, v67, v67
	v_max_f32_e32 v68, v68, v68
	v_max_f32_e32 v64, 0, v64
	v_max_f32_e32 v65, 0, v65
	v_max_f32_e32 v66, 0, v66
	v_max_f32_e32 v67, 0, v67
	v_max_f32_e32 v68, 0, v68
	v_mul_f32_e32 v64, v64, v64
	v_mul_f32_e32 v65, v65, v65
	v_mul_f32_e32 v66, v66, v66
	v_mul_f32_e32 v67, v67, v67
	v_mul_f32_e32 v68, v68, v68
	v_cvt_pk_bf16_f32 v64, v68, v64
	v_cvt_pk_bf16_f32 v65, v65, v66
	v_cvt_pk_bf16_f32 v66, v72, v69
	v_cvt_pk_bf16_f32 v67, v70, v67
	flat_store_dwordx4 v[82:83], v[64:67] offset:256 sc1
.LBB0_253:
	s_or_b64 exec, exec, s[6:7]
	s_nop 0
	v_lshlrev_b64 v[64:65], 13, v[140:141]
	v_lshl_add_u64 v[64:65], s[4:5], 0, v[64:65]
	v_lshl_add_u64 v[64:65], v[142:143], 1, v[64:65]
	s_mov_b64 s[6:7], 0x100000
	v_lshl_add_u64 v[64:65], v[64:65], 0, s[6:7]
	s_and_saveexec_b64 s[6:7], vcc
	s_cbranch_execz .LBB0_255
	v_max_f32_e32 v56, v56, v56
	v_max_f32_e32 v57, v57, v57
	v_max_f32_e32 v58, v58, v58
	v_max_f32_e32 v56, 0, v56
	v_max_f32_e32 v57, 0, v57
	v_max_f32_e32 v58, 0, v58
	v_mul_f32_e32 v66, v56, v56
	v_max_f32_e32 v56, v61, v61
	v_mul_f32_e32 v61, v57, v57
	v_max_f32_e32 v57, v62, v62
	v_mul_f32_e32 v62, v58, v58
	v_max_f32_e32 v58, v63, v63
	v_max_f32_e32 v59, v59, v59
	v_max_f32_e32 v60, v60, v60
	v_max_f32_e32 v56, 0, v56
	v_max_f32_e32 v57, 0, v57
	v_max_f32_e32 v58, 0, v58
	v_max_f32_e32 v59, 0, v59
	v_max_f32_e32 v60, 0, v60
	v_mul_f32_e32 v56, v56, v56
	v_mul_f32_e32 v57, v57, v57
	v_mul_f32_e32 v58, v58, v58
	v_mul_f32_e32 v59, v59, v59
	v_mul_f32_e32 v60, v60, v60
	v_cvt_pk_bf16_f32 v56, v60, v56
	v_cvt_pk_bf16_f32 v57, v57, v58
	v_cvt_pk_bf16_f32 v58, v66, v61
	v_cvt_pk_bf16_f32 v59, v62, v59
	flat_store_dwordx4 v[64:65], v[56:59] sc1
.LBB0_255:
	s_or_b64 exec, exec, s[6:7]
	s_and_saveexec_b64 s[6:7], s[38:39]
	s_cbranch_execz .LBB0_257
	v_max_f32_e32 v48, v48, v48
	v_max_f32_e32 v49, v49, v49
	v_max_f32_e32 v50, v50, v50
	v_max_f32_e32 v48, 0, v48
	v_max_f32_e32 v49, 0, v49
	v_max_f32_e32 v50, 0, v50
	v_mul_f32_e32 v56, v48, v48
	v_max_f32_e32 v48, v53, v53
	v_mul_f32_e32 v53, v49, v49
	v_max_f32_e32 v49, v54, v54
	v_mul_f32_e32 v54, v50, v50
	v_max_f32_e32 v50, v55, v55
	v_max_f32_e32 v51, v51, v51
	v_max_f32_e32 v52, v52, v52
	v_max_f32_e32 v48, 0, v48
	v_max_f32_e32 v49, 0, v49
	v_max_f32_e32 v50, 0, v50
	v_max_f32_e32 v51, 0, v51
	v_max_f32_e32 v52, 0, v52
	v_mul_f32_e32 v48, v48, v48
	v_mul_f32_e32 v49, v49, v49
	v_mul_f32_e32 v50, v50, v50
	v_mul_f32_e32 v51, v51, v51
	v_mul_f32_e32 v52, v52, v52
	v_cvt_pk_bf16_f32 v48, v52, v48
	v_cvt_pk_bf16_f32 v49, v49, v50
	v_cvt_pk_bf16_f32 v50, v56, v53
	v_cvt_pk_bf16_f32 v51, v54, v51
	flat_store_dwordx4 v[64:65], v[48:51] offset:256 sc1
.LBB0_257:
	s_or_b64 exec, exec, s[6:7]
	s_nop 0
	v_lshlrev_b64 v[48:49], 13, v[140:141]
	v_lshl_add_u64 v[48:49], s[4:5], 0, v[48:49]
	v_lshl_add_u64 v[48:49], v[142:143], 1, v[48:49]
	s_mov_b64 s[6:7], 0x120000
	v_lshl_add_u64 v[48:49], v[48:49], 0, s[6:7]
	s_and_saveexec_b64 s[6:7], vcc
	s_cbranch_execz .LBB0_259
	v_max_f32_e32 v40, v40, v40
	v_max_f32_e32 v41, v41, v41
	v_max_f32_e32 v42, v42, v42
	v_max_f32_e32 v40, 0, v40
	v_max_f32_e32 v41, 0, v41
	v_max_f32_e32 v42, 0, v42
	v_mul_f32_e32 v50, v40, v40
	v_max_f32_e32 v40, v45, v45
	v_mul_f32_e32 v45, v41, v41
	v_max_f32_e32 v41, v46, v46
	v_mul_f32_e32 v46, v42, v42
	v_max_f32_e32 v42, v47, v47
	v_max_f32_e32 v43, v43, v43
	v_max_f32_e32 v44, v44, v44
	v_max_f32_e32 v40, 0, v40
	v_max_f32_e32 v41, 0, v41
	v_max_f32_e32 v42, 0, v42
	v_max_f32_e32 v43, 0, v43
	v_max_f32_e32 v44, 0, v44
	v_mul_f32_e32 v40, v40, v40
	v_mul_f32_e32 v41, v41, v41
	v_mul_f32_e32 v42, v42, v42
	v_mul_f32_e32 v43, v43, v43
	v_mul_f32_e32 v44, v44, v44
	v_cvt_pk_bf16_f32 v40, v44, v40
	v_cvt_pk_bf16_f32 v41, v41, v42
	v_cvt_pk_bf16_f32 v42, v50, v45
	v_cvt_pk_bf16_f32 v43, v46, v43
	flat_store_dwordx4 v[48:49], v[40:43] sc1
.LBB0_259:
	s_or_b64 exec, exec, s[6:7]
	s_and_saveexec_b64 s[6:7], s[38:39]
	s_cbranch_execz .LBB0_261
	v_max_f32_e32 v32, v32, v32
	v_max_f32_e32 v33, v33, v33
	v_max_f32_e32 v34, v34, v34
	v_max_f32_e32 v32, 0, v32
	v_max_f32_e32 v33, 0, v33
	v_max_f32_e32 v34, 0, v34
	v_mul_f32_e32 v40, v32, v32
	v_max_f32_e32 v32, v37, v37
	v_mul_f32_e32 v37, v33, v33
	v_max_f32_e32 v33, v38, v38
	v_mul_f32_e32 v38, v34, v34
	v_max_f32_e32 v34, v39, v39
	v_max_f32_e32 v35, v35, v35
	v_max_f32_e32 v36, v36, v36
	v_max_f32_e32 v32, 0, v32
	v_max_f32_e32 v33, 0, v33
	v_max_f32_e32 v34, 0, v34
	v_max_f32_e32 v35, 0, v35
	v_max_f32_e32 v36, 0, v36
	v_mul_f32_e32 v32, v32, v32
	v_mul_f32_e32 v33, v33, v33
	v_mul_f32_e32 v34, v34, v34
	v_mul_f32_e32 v35, v35, v35
	v_mul_f32_e32 v36, v36, v36
	v_cvt_pk_bf16_f32 v32, v36, v32
	v_cvt_pk_bf16_f32 v33, v33, v34
	v_cvt_pk_bf16_f32 v34, v40, v37
	v_cvt_pk_bf16_f32 v35, v38, v35
	flat_store_dwordx4 v[48:49], v[32:35] offset:256 sc1
.LBB0_261:
	s_or_b64 exec, exec, s[6:7]
	s_nop 0
	v_lshlrev_b64 v[32:33], 13, v[140:141]
	v_lshl_add_u64 v[32:33], s[4:5], 0, v[32:33]
	v_lshl_add_u64 v[32:33], v[142:143], 1, v[32:33]
	s_mov_b64 s[6:7], 0x140000
	v_lshl_add_u64 v[32:33], v[32:33], 0, s[6:7]
	s_and_saveexec_b64 s[6:7], vcc
	s_cbranch_execz .LBB0_263
	v_max_f32_e32 v24, v24, v24
	v_max_f32_e32 v25, v25, v25
	v_max_f32_e32 v26, v26, v26
	v_max_f32_e32 v24, 0, v24
	v_max_f32_e32 v25, 0, v25
	v_max_f32_e32 v26, 0, v26
	v_mul_f32_e32 v34, v24, v24
	v_max_f32_e32 v24, v29, v29
	v_mul_f32_e32 v29, v25, v25
	v_max_f32_e32 v25, v30, v30
	v_mul_f32_e32 v30, v26, v26
	v_max_f32_e32 v26, v31, v31
	v_max_f32_e32 v27, v27, v27
	v_max_f32_e32 v28, v28, v28
	v_max_f32_e32 v24, 0, v24
	v_max_f32_e32 v25, 0, v25
	v_max_f32_e32 v26, 0, v26
	v_max_f32_e32 v27, 0, v27
	v_max_f32_e32 v28, 0, v28
	v_mul_f32_e32 v24, v24, v24
	v_mul_f32_e32 v25, v25, v25
	v_mul_f32_e32 v26, v26, v26
	v_mul_f32_e32 v27, v27, v27
	v_mul_f32_e32 v28, v28, v28
	v_cvt_pk_bf16_f32 v24, v28, v24
	v_cvt_pk_bf16_f32 v25, v25, v26
	v_cvt_pk_bf16_f32 v26, v34, v29
	v_cvt_pk_bf16_f32 v27, v30, v27
	flat_store_dwordx4 v[32:33], v[24:27] sc1
.LBB0_263:
	s_or_b64 exec, exec, s[6:7]
	s_and_saveexec_b64 s[6:7], s[38:39]
	s_cbranch_execz .LBB0_265
	v_max_f32_e32 v16, v16, v16
	v_max_f32_e32 v17, v17, v17
	v_max_f32_e32 v18, v18, v18
	v_max_f32_e32 v16, 0, v16
	v_max_f32_e32 v17, 0, v17
	v_max_f32_e32 v18, 0, v18
	v_mul_f32_e32 v24, v16, v16
	v_max_f32_e32 v16, v21, v21
	v_mul_f32_e32 v21, v17, v17
	v_max_f32_e32 v17, v22, v22
	v_mul_f32_e32 v22, v18, v18
	v_max_f32_e32 v18, v23, v23
	v_max_f32_e32 v19, v19, v19
	v_max_f32_e32 v20, v20, v20
	v_max_f32_e32 v16, 0, v16
	v_max_f32_e32 v17, 0, v17
	v_max_f32_e32 v18, 0, v18
	v_max_f32_e32 v19, 0, v19
	v_max_f32_e32 v20, 0, v20
	v_mul_f32_e32 v16, v16, v16
	v_mul_f32_e32 v17, v17, v17
	v_mul_f32_e32 v18, v18, v18
	v_mul_f32_e32 v19, v19, v19
	v_mul_f32_e32 v20, v20, v20
	v_cvt_pk_bf16_f32 v16, v20, v16
	v_cvt_pk_bf16_f32 v17, v17, v18
	v_cvt_pk_bf16_f32 v18, v24, v21
	v_cvt_pk_bf16_f32 v19, v22, v19
	flat_store_dwordx4 v[32:33], v[16:19] offset:256 sc1

.LBB0_268:
	v_max_f32_e32 v8, v8, v8
	v_max_f32_e32 v9, v9, v9
	v_max_f32_e32 v10, v10, v10
	v_max_f32_e32 v8, 0, v8
	v_max_f32_e32 v9, 0, v9
	v_max_f32_e32 v10, 0, v10
	v_mul_f32_e32 v18, v8, v8
	v_max_f32_e32 v8, v13, v13
	v_mul_f32_e32 v13, v9, v9
	v_max_f32_e32 v9, v14, v14
	v_mul_f32_e32 v14, v10, v10
	v_max_f32_e32 v10, v15, v15
	v_max_f32_e32 v11, v11, v11
	v_max_f32_e32 v12, v12, v12
	v_max_f32_e32 v8, 0, v8
	v_max_f32_e32 v9, 0, v9
	v_max_f32_e32 v10, 0, v10
	v_max_f32_e32 v11, 0, v11
	v_max_f32_e32 v12, 0, v12
	v_mul_f32_e32 v8, v8, v8
	v_mul_f32_e32 v9, v9, v9
	v_mul_f32_e32 v10, v10, v10
	v_mul_f32_e32 v11, v11, v11
	v_mul_f32_e32 v12, v12, v12
	v_cvt_pk_bf16_f32 v8, v12, v8
	v_cvt_pk_bf16_f32 v9, v9, v10
	v_cvt_pk_bf16_f32 v10, v18, v13
	v_cvt_pk_bf16_f32 v11, v14, v11
	flat_store_dwordx4 v[16:17], v[8:11] sc1
	s_or_b64 exec, exec, s[6:7]
	s_and_saveexec_b64 s[6:7], s[38:39]
	s_cbranch_execz .LBB0_267
.LBB0_269:
	v_max_f32_e32 v0, v0, v0
	v_max_f32_e32 v1, v1, v1
	v_max_f32_e32 v2, v2, v2
	v_max_f32_e32 v0, 0, v0
	v_max_f32_e32 v1, 0, v1
	v_max_f32_e32 v2, 0, v2
	v_mul_f32_e32 v8, v0, v0
	v_max_f32_e32 v0, v5, v5
	v_mul_f32_e32 v5, v1, v1
	v_max_f32_e32 v1, v6, v6
	v_mul_f32_e32 v6, v2, v2
	v_max_f32_e32 v2, v7, v7
	v_max_f32_e32 v3, v3, v3
	v_max_f32_e32 v4, v4, v4
	v_max_f32_e32 v0, 0, v0
	v_max_f32_e32 v1, 0, v1
	v_max_f32_e32 v2, 0, v2
	v_max_f32_e32 v3, 0, v3
	v_max_f32_e32 v4, 0, v4
	v_mul_f32_e32 v0, v0, v0
	v_mul_f32_e32 v1, v1, v1
	v_mul_f32_e32 v2, v2, v2
	v_mul_f32_e32 v3, v3, v3
	v_mul_f32_e32 v4, v4, v4
	v_cvt_pk_bf16_f32 v0, v4, v0
	v_cvt_pk_bf16_f32 v1, v1, v2
	v_cvt_pk_bf16_f32 v2, v8, v5
	v_cvt_pk_bf16_f32 v3, v6, v3
	flat_store_dwordx4 v[16:17], v[0:3] offset:256 sc1
	s_or_b64 exec, exec, s[6:7]
	s_andn2_b64 vcc, exec, s[36:37]
	s_mov_b64 s[6:7], -1
	s_cbranch_vccnz .LBB0_230

.LBB0_392:
	v_mbcnt_lo_u32_b32 v141, -1, 0
	v_mbcnt_hi_u32_b32 v141, -1, v141
	s_lshl_b32 s0, s78, 8
	v_ashrrev_i32_e32 v140, 1, v141
	v_and_or_b32 v141, v141, 15, s80
	v_lshl_add_u32 v142, s77, 8, v141
	v_and_b32_e32 v140, -8, v140
	s_or_b32 s0, s0, s81
	v_ashrrev_i32_e32 v143, 31, v142
	v_add_u32_e32 v140, s0, v140
	v_lshlrev_b64 v[144:145], 11, v[142:143]
	v_ashrrev_i32_e32 v141, 31, v140
	v_lshl_add_u64 v[144:145], s[14:15], 0, v[144:145]
	v_lshl_add_u64 v[144:145], v[140:141], 1, v[144:145]
	v_cmp_gt_i32_e32 vcc, s90, v140
	s_and_saveexec_b64 s[0:1], vcc
	s_cbranch_execz .LBB0_394
	v_cvt_pk_bf16_f32 v126, v126, v127
	v_cvt_pk_bf16_f32 v127, v128, v129
	v_cvt_pk_bf16_f32 v128, v122, v123
	v_cvt_pk_bf16_f32 v129, v124, v125
	flat_store_dwordx4 v[144:145], v[126:129] sc1
.LBB0_394:
	s_or_b64 exec, exec, s[0:1]
	s_movk_i32 s0, 0x380
	v_cmp_gt_i32_e64 s[0:1], s0, v140
	s_and_saveexec_b64 s[6:7], s[0:1]
	s_cbranch_execz .LBB0_396
	v_cvt_pk_bf16_f32 v118, v118, v119
	v_cvt_pk_bf16_f32 v119, v120, v121
	v_cvt_pk_bf16_f32 v120, v110, v111
	v_cvt_pk_bf16_f32 v121, v112, v113
	flat_store_dwordx4 v[144:145], v[118:121] offset:256 sc1
.LBB0_396:
	s_or_b64 exec, exec, s[6:7]
	v_or_b32_e32 v110, 16, v142
	v_ashrrev_i32_e32 v111, 31, v110
	v_lshlrev_b64 v[110:111], 11, v[110:111]
	v_lshl_add_u64 v[110:111], s[14:15], 0, v[110:111]
	v_lshl_add_u64 v[110:111], v[140:141], 1, v[110:111]
	s_and_saveexec_b64 s[6:7], vcc
	s_cbranch_execz .LBB0_398
	v_cvt_pk_bf16_f32 v112, v114, v115
	v_cvt_pk_bf16_f32 v113, v116, v117
	v_cvt_pk_bf16_f32 v114, v106, v107
	v_cvt_pk_bf16_f32 v115, v108, v109
	flat_store_dwordx4 v[110:111], v[112:115] sc1
.LBB0_398:
	s_or_b64 exec, exec, s[6:7]
	s_and_saveexec_b64 s[6:7], s[0:1]
	s_cbranch_execz .LBB0_400
	v_cvt_pk_bf16_f32 v102, v102, v103
	v_cvt_pk_bf16_f32 v103, v104, v105
	v_cvt_pk_bf16_f32 v104, v94, v95
	v_cvt_pk_bf16_f32 v105, v96, v97
	flat_store_dwordx4 v[110:111], v[102:105] offset:256 sc1
.LBB0_400:
	s_or_b64 exec, exec, s[6:7]
	v_or_b32_e32 v94, 32, v142
	v_ashrrev_i32_e32 v95, 31, v94
	v_lshlrev_b64 v[94:95], 11, v[94:95]
	v_lshl_add_u64 v[94:95], s[14:15], 0, v[94:95]
	v_lshl_add_u64 v[94:95], v[140:141], 1, v[94:95]
	s_and_saveexec_b64 s[6:7], vcc
	s_cbranch_execz .LBB0_402
	v_cvt_pk_bf16_f32 v96, v98, v99
	v_cvt_pk_bf16_f32 v97, v100, v101
	v_cvt_pk_bf16_f32 v98, v90, v91
	v_cvt_pk_bf16_f32 v99, v92, v93
	flat_store_dwordx4 v[94:95], v[96:99] sc1
.LBB0_402:
	s_or_b64 exec, exec, s[6:7]
	s_and_saveexec_b64 s[6:7], s[0:1]
	s_cbranch_execz .LBB0_404
	v_cvt_pk_bf16_f32 v86, v86, v87
	v_cvt_pk_bf16_f32 v87, v88, v89
	v_cvt_pk_bf16_f32 v88, v76, v77
	v_cvt_pk_bf16_f32 v89, v78, v79
	flat_store_dwordx4 v[94:95], v[86:89] offset:256 sc1
.LBB0_404:
	s_or_b64 exec, exec, s[6:7]
	v_or_b32_e32 v76, 48, v142
	v_ashrrev_i32_e32 v77, 31, v76
	v_lshlrev_b64 v[76:77], 11, v[76:77]
	v_lshl_add_u64 v[76:77], s[14:15], 0, v[76:77]
	v_lshl_add_u64 v[76:77], v[140:141], 1, v[76:77]
	s_and_saveexec_b64 s[6:7], vcc
	s_cbranch_execz .LBB0_406
	v_cvt_pk_bf16_f32 v82, v82, v83
	v_cvt_pk_bf16_f32 v83, v84, v85
	v_cvt_pk_bf16_f32 v84, v72, v73
	v_cvt_pk_bf16_f32 v85, v74, v75
	flat_store_dwordx4 v[76:77], v[82:85] sc1
.LBB0_406:
	s_or_b64 exec, exec, s[6:7]
	s_and_saveexec_b64 s[6:7], s[0:1]
	s_cbranch_execz .LBB0_408
	v_cvt_pk_bf16_f32 v68, v68, v69
	v_cvt_pk_bf16_f32 v69, v70, v71
	v_cvt_pk_bf16_f32 v70, v64, v65
	v_cvt_pk_bf16_f32 v71, v66, v67
	flat_store_dwordx4 v[76:77], v[68:71] offset:256 sc1
.LBB0_408:
	s_or_b64 exec, exec, s[6:7]
	v_lshlrev_b64 v[64:65], 11, v[142:143]
	v_lshl_add_u64 v[64:65], s[14:15], 0, v[64:65]
	v_lshl_add_u64 v[64:65], v[140:141], 1, v[64:65]
	s_mov_b64 s[6:7], 0x40000
	v_lshl_add_u64 v[64:65], v[64:65], 0, s[6:7]
	s_and_saveexec_b64 s[6:7], vcc
	s_cbranch_execz .LBB0_410
	v_cvt_pk_bf16_f32 v60, v60, v61
	v_cvt_pk_bf16_f32 v61, v62, v63
	v_cvt_pk_bf16_f32 v62, v56, v57
	v_cvt_pk_bf16_f32 v63, v58, v59
	flat_store_dwordx4 v[64:65], v[60:63] sc1
.LBB0_410:
	s_or_b64 exec, exec, s[6:7]
	s_and_saveexec_b64 s[6:7], s[0:1]
	s_cbranch_execz .LBB0_412
	v_cvt_pk_bf16_f32 v52, v52, v53
	v_cvt_pk_bf16_f32 v53, v54, v55
	v_cvt_pk_bf16_f32 v54, v44, v45
	v_cvt_pk_bf16_f32 v55, v46, v47
	flat_store_dwordx4 v[64:65], v[52:55] offset:256 sc1
.LBB0_412:
	s_or_b64 exec, exec, s[6:7]
	v_lshlrev_b64 v[44:45], 11, v[142:143]
	v_lshl_add_u64 v[44:45], s[14:15], 0, v[44:45]
	v_lshl_add_u64 v[44:45], v[140:141], 1, v[44:45]
	s_mov_b64 s[6:7], 0x48000
	v_lshl_add_u64 v[44:45], v[44:45], 0, s[6:7]
	s_and_saveexec_b64 s[6:7], vcc
	s_cbranch_execz .LBB0_414
	v_cvt_pk_bf16_f32 v46, v48, v49
	v_cvt_pk_bf16_f32 v47, v50, v51
	v_cvt_pk_bf16_f32 v48, v40, v41
	v_cvt_pk_bf16_f32 v49, v42, v43
	flat_store_dwordx4 v[44:45], v[46:49] sc1
.LBB0_414:
	s_or_b64 exec, exec, s[6:7]
	s_and_saveexec_b64 s[6:7], s[0:1]
	s_cbranch_execz .LBB0_416
	v_cvt_pk_bf16_f32 v36, v36, v37
	v_cvt_pk_bf16_f32 v37, v38, v39
	v_cvt_pk_bf16_f32 v38, v28, v29
	v_cvt_pk_bf16_f32 v39, v30, v31
	flat_store_dwordx4 v[44:45], v[36:39] offset:256 sc1
.LBB0_416:
	s_or_b64 exec, exec, s[6:7]
	v_lshlrev_b64 v[28:29], 11, v[142:143]
	v_lshl_add_u64 v[28:29], s[14:15], 0, v[28:29]
	v_lshl_add_u64 v[28:29], v[140:141], 1, v[28:29]
	s_mov_b64 s[6:7], 0x50000
	v_lshl_add_u64 v[28:29], v[28:29], 0, s[6:7]
	s_and_saveexec_b64 s[6:7], vcc
	s_cbranch_execz .LBB0_418
	v_cvt_pk_bf16_f32 v30, v32, v33
	v_cvt_pk_bf16_f32 v31, v34, v35
	v_cvt_pk_bf16_f32 v32, v24, v25
	v_cvt_pk_bf16_f32 v33, v26, v27
	flat_store_dwordx4 v[28:29], v[30:33] sc1
.LBB0_418:
	s_or_b64 exec, exec, s[6:7]
	s_and_saveexec_b64 s[6:7], s[0:1]
	s_cbranch_execz .LBB0_420
	v_cvt_pk_bf16_f32 v20, v20, v21
	v_cvt_pk_bf16_f32 v21, v22, v23
	v_cvt_pk_bf16_f32 v22, v12, v13
	v_cvt_pk_bf16_f32 v23, v14, v15
	flat_store_dwordx4 v[28:29], v[20:23] offset:256 sc1

.LBB0_423:
	v_cvt_pk_bf16_f32 v14, v16, v17
	v_cvt_pk_bf16_f32 v15, v18, v19
	v_cvt_pk_bf16_f32 v16, v8, v9
	v_cvt_pk_bf16_f32 v17, v10, v11
	flat_store_dwordx4 v[12:13], v[14:17] sc1
	s_or_b64 exec, exec, s[6:7]
	s_and_saveexec_b64 s[6:7], s[0:1]
	s_cbranch_execz .LBB0_422
.LBB0_424:
	v_cvt_pk_bf16_f32 v4, v4, v5
	v_cvt_pk_bf16_f32 v5, v6, v7
	v_cvt_pk_bf16_f32 v6, v0, v1
	v_cvt_pk_bf16_f32 v7, v2, v3
	flat_store_dwordx4 v[12:13], v[4:7] offset:256 sc1
	s_or_b64 exec, exec, s[6:7]
	s_andn2_b64 vcc, exec, s[36:37]
	s_mov_b64 s[0:1], -1
	s_cbranch_vccnz .LBB0_385

.Lk0_e1:
	v_ashrrev_i32_e32 v140, 1, v141
	v_and_or_b32 v141, v141, 15, s64
	v_and_b32_e32 v140, -8, v140
	s_or_b32 s0, s0, s65
	v_lshl_add_u32 v146, s77, 8, v141
	v_mov_b64_e32 v[142:143], s[8:9]
	v_add_u32_e32 v140, s0, v140
	v_mad_i64_i32 v[142:143], s[0:1], v146, s24, v[142:143]
	v_ashrrev_i32_e32 v141, 31, v140
	s_movk_i32 s0, 0x7c0
	v_lshl_add_u64 v[142:143], v[140:141], 1, v[142:143]
	v_cmp_gt_i32_e32 vcc, s0, v140
	s_and_saveexec_b64 s[0:1], vcc
	s_cbranch_execz .LBB0_482
	v_cvt_pk_bf16_f32 v126, v126, v127
	v_cvt_pk_bf16_f32 v127, v128, v129
	v_cvt_pk_bf16_f32 v128, v122, v123
	v_cvt_pk_bf16_f32 v129, v124, v125
	flat_store_dwordx4 v[142:143], v[126:129] sc1
.LBB0_482:
	s_or_b64 exec, exec, s[0:1]
	s_movk_i32 s0, 0x740
	s_cmp_lg_u32 s101, 1
	s_cselect_b32 s0, s0, 0
	v_cmp_gt_i32_e64 s[0:1], s0, v140
	s_and_saveexec_b64 s[6:7], s[0:1]
	s_cbranch_execz .LBB0_484
	v_cvt_pk_bf16_f32 v118, v118, v119
	v_cvt_pk_bf16_f32 v119, v120, v121
	v_cvt_pk_bf16_f32 v120, v110, v111
	v_cvt_pk_bf16_f32 v121, v112, v113
	flat_store_dwordx4 v[142:143], v[118:121] offset:256 sc1
.LBB0_484:
	s_or_b64 exec, exec, s[6:7]
	v_or_b32_e32 v112, 16, v146
	v_mov_b64_e32 v[110:111], s[8:9]
	v_mad_i64_i32 v[110:111], s[6:7], v112, s24, v[110:111]
	v_lshl_add_u64 v[110:111], v[140:141], 1, v[110:111]
	s_and_saveexec_b64 s[6:7], vcc
	s_cbranch_execz .LBB0_486
	v_cvt_pk_bf16_f32 v112, v114, v115
	v_cvt_pk_bf16_f32 v113, v116, v117
	v_cvt_pk_bf16_f32 v114, v106, v107
	v_cvt_pk_bf16_f32 v115, v108, v109
	flat_store_dwordx4 v[110:111], v[112:115] sc1

.LBB0_488:
	s_or_b64 exec, exec, s[6:7]
	v_or_b32_e32 v96, 32, v146
	v_mov_b64_e32 v[94:95], s[8:9]
	v_mad_i64_i32 v[94:95], s[6:7], v96, s24, v[94:95]
	v_lshl_add_u64 v[94:95], v[140:141], 1, v[94:95]
	s_and_saveexec_b64 s[6:7], vcc
	s_cbranch_execz .LBB0_490
	v_cvt_pk_bf16_f32 v96, v98, v99
	v_cvt_pk_bf16_f32 v97, v100, v101
	v_cvt_pk_bf16_f32 v98, v90, v91
	v_cvt_pk_bf16_f32 v99, v92, v93
	flat_store_dwordx4 v[94:95], v[96:99] sc1

.LBB0_492:
	s_or_b64 exec, exec, s[6:7]
	v_or_b32_e32 v78, 48, v146
	v_mov_b64_e32 v[76:77], s[8:9]
	v_mad_i64_i32 v[76:77], s[6:7], v78, s24, v[76:77]
	v_lshl_add_u64 v[76:77], v[140:141], 1, v[76:77]
	s_and_saveexec_b64 s[6:7], vcc
	s_cbranch_execz .LBB0_494
	v_cvt_pk_bf16_f32 v82, v82, v83
	v_cvt_pk_bf16_f32 v83, v84, v85
	v_cvt_pk_bf16_f32 v84, v72, v73
	v_cvt_pk_bf16_f32 v85, v74, v75
	flat_store_dwordx4 v[76:77], v[82:85] sc1

.LBB0_496:
	s_or_b64 exec, exec, s[6:7]
	v_add_u32_e32 v66, 0x80, v146
	v_mov_b64_e32 v[64:65], s[8:9]
	v_mad_i64_i32 v[64:65], s[6:7], v66, s24, v[64:65]
	v_lshl_add_u64 v[64:65], v[140:141], 1, v[64:65]
	s_and_saveexec_b64 s[6:7], vcc
	s_cbranch_execz .LBB0_498
	v_cvt_pk_bf16_f32 v60, v60, v61
	v_cvt_pk_bf16_f32 v61, v62, v63
	v_cvt_pk_bf16_f32 v62, v56, v57
	v_cvt_pk_bf16_f32 v63, v58, v59
	flat_store_dwordx4 v[64:65], v[60:63] sc1

.LBB0_500:
	s_or_b64 exec, exec, s[6:7]
	v_add_u32_e32 v46, 0x90, v146
	v_mov_b64_e32 v[44:45], s[8:9]
	v_mad_i64_i32 v[44:45], s[6:7], v46, s24, v[44:45]
	v_lshl_add_u64 v[44:45], v[140:141], 1, v[44:45]
	s_and_saveexec_b64 s[6:7], vcc
	s_cbranch_execz .LBB0_502
	v_cvt_pk_bf16_f32 v46, v48, v49
	v_cvt_pk_bf16_f32 v47, v50, v51
	v_cvt_pk_bf16_f32 v48, v40, v41
	v_cvt_pk_bf16_f32 v49, v42, v43
	flat_store_dwordx4 v[44:45], v[46:49] sc1

.LBB0_504:
	s_or_b64 exec, exec, s[6:7]
	v_add_u32_e32 v30, 0xa0, v146
	v_mov_b64_e32 v[28:29], s[8:9]
	v_mad_i64_i32 v[28:29], s[6:7], v30, s24, v[28:29]
	v_lshl_add_u64 v[28:29], v[140:141], 1, v[28:29]
	s_and_saveexec_b64 s[6:7], vcc
	s_cbranch_execz .LBB0_506
	v_cvt_pk_bf16_f32 v30, v32, v33
	v_cvt_pk_bf16_f32 v31, v34, v35
	v_cvt_pk_bf16_f32 v32, v24, v25
	v_cvt_pk_bf16_f32 v33, v26, v27
	flat_store_dwordx4 v[28:29], v[30:33] sc1
